# attention: row-sum accumulated in two independent v_add chains (on top of v7)
# speedup vs baseline: 1.0045x; 1.0045x over previous
.Latt_prio_done:
.LBB0_674:
	s_add_i32 s2, s67, -1
	s_and_b32 s2, s2, 3
	s_mulk_i32 s2, 0x3400
	s_and_b32 s71, s67, 2
	s_add_i32 s2, s2, 0
	s_xor_b32 s3, s71, 2
	v_add_u32_e32 v0, s2, v192
	s_mulk_i32 s3, 0x2400
	s_waitcnt vmcnt(5)
	ds_write_b128 v0, v[152:155]
	v_add_u32_e32 v0, s2, v185
	s_add_i32 s2, s67, 5
	s_waitcnt vmcnt(4)
	ds_write_b128 v0, v[156:159] offset:128
	v_add_u32_e32 v0, s3, v193
	s_min_i32 s46, s2, s66
	s_add_i32 s2, s67, 4
	v_add_u32_e32 v0, 0xd000, v0
	s_min_i32 s2, s2, s66
	s_lshl_b64 s[4:5], s[46:47], 16
	s_mov_b32 s3, s47
	s_waitcnt vmcnt(3)
	ds_write2_b64 v0, v[172:173], v[174:175] offset1:2
	v_lshl_add_u64 v[2:3], v[186:187], 0, s[4:5]
	s_lshl_b64 s[4:5], s[46:47], 12
	s_lshl_b64 s[2:3], s[2:3], 7
	v_lshl_add_u64 v[4:5], v[188:189], 0, s[4:5]
	global_load_dwordx4 v[152:155], v[2:3], off
	global_load_dwordx4 v[156:159], v[4:5], off
	v_lshl_add_u64 v[2:3], v[190:191], 0, s[2:3]
	global_load_dwordx4 v[172:175], v[2:3], off
	s_add_i32 s70, s67, 1
	s_and_b32 s69, s70, 3
	s_cmp_gt_i32 s67, s65
	s_cbranch_scc1 .LBB0_685
	s_mul_i32 s2, s69, 0x3400
	v_add_u32_e32 v0, s2, v196
	ds_read_b128 v[2:5], v0
	ds_read_b128 v[6:9], v0 offset:6656
	s_waitcnt lgkmcnt(1)
	v_mfma_f32_32x32x16_bf16 v[112:127], v[2:5], v[128:131], v[48:63]
	ds_read_b128 v[10:13], v0 offset:32
	ds_read_b128 v[202:205], v0 offset:6688
	v_add_f32_e32 v211, 0, v80
	v_add_f32_e32 v210, 0, v81
	v_cvt_pk_bf16_f32 v176, v80, v81
	s_waitcnt lgkmcnt(2)
	v_mfma_f32_32x32x16_bf16 v[96:111], v[6:9], v[128:131], v[48:63]
	v_add_f32_e32 v211, v82, v211
	v_add_f32_e32 v210, v83, v210
	v_add_f32_e32 v211, v84, v211
	v_cvt_pk_bf16_f32 v177, v82, v83
	s_waitcnt lgkmcnt(1)
	v_mfma_f32_32x32x16_bf16 v[112:127], v[10:13], v[132:135], v[112:127]
	ds_read_b128 v[2:5], v0 offset:64
	ds_read_b128 v[6:9], v0 offset:6720
	v_add_f32_e32 v210, v85, v210
	v_add_f32_e32 v211, v86, v211
	v_add_f32_e32 v210, v87, v210
	v_cvt_pk_bf16_f32 v178, v84, v85
	v_cvt_pk_bf16_f32 v179, v86, v87
	s_waitcnt lgkmcnt(2)
	v_mfma_f32_32x32x16_bf16 v[96:111], v[202:205], v[132:135], v[96:111]
	v_add_f32_e32 v211, v88, v211
	v_add_f32_e32 v210, v89, v210
	v_cvt_pk_bf16_f32 v10, v88, v89
	s_waitcnt lgkmcnt(1)
	v_mfma_f32_32x32x16_bf16 v[112:127], v[2:5], v[136:139], v[112:127]
	ds_read_b128 v[80:83], v0 offset:96
	ds_read_b128 v[202:205], v0 offset:6752
	v_add_f32_e32 v211, v90, v211
	v_add_f32_e32 v210, v91, v210
	v_add_f32_e32 v211, v92, v211
	v_cvt_pk_bf16_f32 v11, v90, v91
	s_waitcnt lgkmcnt(2)
	v_mfma_f32_32x32x16_bf16 v[96:111], v[6:9], v[136:139], v[96:111]
	v_add_f32_e32 v210, v93, v210
	v_add_f32_e32 v211, v94, v211
	v_add_f32_e32 v210, v95, v210
	v_cvt_pk_bf16_f32 v12, v92, v93
	v_cvt_pk_bf16_f32 v13, v94, v95
	s_waitcnt lgkmcnt(1)
	v_mfma_f32_32x32x16_bf16 v[112:127], v[80:83], v[140:143], v[112:127]
	ds_read_b128 v[2:5], v0 offset:128
	ds_read_b128 v[206:209], v0 offset:6784
	v_add_f32_e32 v211, v16, v211
	v_add_f32_e32 v210, v17, v210
	v_cvt_pk_bf16_f32 v6, v16, v17
	s_waitcnt lgkmcnt(2)
	v_mfma_f32_32x32x16_bf16 v[96:111], v[202:205], v[140:143], v[96:111]
	v_add_f32_e32 v211, v18, v211
	v_add_f32_e32 v210, v19, v210
	v_add_f32_e32 v211, v20, v211
	v_cvt_pk_bf16_f32 v7, v18, v19
	s_waitcnt lgkmcnt(1)
	v_mfma_f32_32x32x16_bf16 v[112:127], v[2:5], v[144:147], v[112:127]
	ds_read_b128 v[14:17], v0 offset:160
	ds_read_b128 v[80:83], v0 offset:6816
	v_add_f32_e32 v210, v21, v210
	v_add_f32_e32 v211, v22, v211
	v_add_f32_e32 v210, v23, v210
	v_cvt_pk_bf16_f32 v8, v20, v21
	v_cvt_pk_bf16_f32 v9, v22, v23
	s_waitcnt lgkmcnt(2)
	v_mfma_f32_32x32x16_bf16 v[96:111], v[206:209], v[144:147], v[96:111]
	v_add_f32_e32 v211, v24, v211
	v_add_f32_e32 v210, v25, v210
	v_cvt_pk_bf16_f32 v2, v24, v25
	s_waitcnt lgkmcnt(1)
	v_mfma_f32_32x32x16_bf16 v[112:127], v[14:17], v[148:151], v[112:127]
	v_add_f32_e32 v211, v26, v211
	v_add_f32_e32 v210, v27, v210
	v_add_f32_e32 v211, v28, v211
	v_cvt_pk_bf16_f32 v3, v26, v27
	s_waitcnt lgkmcnt(0)
	v_mfma_f32_32x32x16_bf16 v[96:111], v[80:83], v[148:151], v[96:111]
	v_add_f32_e32 v210, v29, v210
	v_add_f32_e32 v211, v30, v211
	v_add_f32_e32 v210, v31, v210
	v_add_f32_e32 v0, v210, v211
	v_cvt_pk_bf16_f32 v4, v28, v29
	v_cvt_pk_bf16_f32 v5, v30, v31
	s_mul_i32 s4, s71, 0x2400
	v_add_u32_e32 v206, s4, v200
	ds_read_b128 v[16:19], v206 offset:53248
	ds_read_b128 v[202:205], v206 offset:57856
	s_cmp_ge_i32 s67, s65
	v_add_f32_e32 v201, v201, v0
	s_cbranch_scc1 .LBB0_682
	s_sub_i32 s2, s68, 64
	s_cmp_le_i32 s2, s63
	s_cbranch_scc1 .LBB0_680
	v_add_u32_e32 v0, s68, v197
	v_add_u32_e32 v15, 0xffffffa1, v0
	v_add_u32_e32 v14, 0xffffff81, v0
	v_cmp_le_i32_e64 s[2:3], v15, v184
	v_cmp_le_i32_e32 vcc, v14, v184
	s_nop 0
	v_cndmask_b32_e64 v96, v194, v96, s[2:3]
	v_cmp_lt_i32_e64 s[2:3], v14, v184
	v_add_u32_e32 v14, 0xffffffa2, v0
	v_cmp_le_i32_e64 s[4:5], v14, v184
	v_add_u32_e32 v14, 0xffffff83, v0
	s_nop 0
	v_cndmask_b32_e64 v97, v194, v97, s[4:5]
	v_cmp_le_i32_e64 s[4:5], v14, v184
	v_add_u32_e32 v14, 0xffffffa3, v0
	v_cmp_le_i32_e64 s[6:7], v14, v184
	v_add_u32_e32 v14, 0xffffff84, v0
	s_nop 0
	v_cndmask_b32_e64 v98, v194, v98, s[6:7]
	v_cmp_le_i32_e64 s[6:7], v14, v184
	v_add_u32_e32 v14, 0xffffffa4, v0
	v_cmp_le_i32_e64 s[8:9], v14, v184
	v_add_u32_e32 v14, 0xffffff89, v0
	s_nop 0
	v_cndmask_b32_e64 v99, v194, v99, s[8:9]
	v_cmp_le_i32_e64 s[8:9], v14, v184
	v_add_u32_e32 v14, 0xffffffa9, v0
	v_cmp_le_i32_e64 s[10:11], v14, v184
	v_add_u32_e32 v14, 0xffffff8a, v0
	s_nop 0
	v_cndmask_b32_e64 v100, v194, v100, s[10:11]
	v_cmp_le_i32_e64 s[10:11], v14, v184
	v_add_u32_e32 v14, 0xffffffaa, v0
	v_cmp_le_i32_e64 s[12:13], v14, v184
	v_add_u32_e32 v14, 0xffffff8b, v0
	s_nop 0
	v_cndmask_b32_e64 v101, v194, v101, s[12:13]
	v_cmp_le_i32_e64 s[12:13], v14, v184
	v_add_u32_e32 v14, 0xffffffab, v0
	v_cmp_le_i32_e64 s[14:15], v14, v184
	v_add_u32_e32 v14, 0xffffff8c, v0
	s_nop 0
	v_cndmask_b32_e64 v102, v194, v102, s[14:15]
	v_cmp_le_i32_e64 s[14:15], v14, v184
	v_add_u32_e32 v14, 0xffffffac, v0
	v_cmp_le_i32_e64 s[16:17], v14, v184
	v_add_u32_e32 v14, 0xffffff91, v0
	s_nop 0
	v_cndmask_b32_e64 v103, v194, v103, s[16:17]
	v_cmp_le_i32_e64 s[16:17], v14, v184
	v_add_u32_e32 v14, 0xffffffb1, v0
	v_cmp_le_i32_e64 s[18:19], v14, v184
	v_add_u32_e32 v14, 0xffffff92, v0
	s_nop 0
	v_cndmask_b32_e64 v104, v194, v104, s[18:19]
	v_cmp_le_i32_e64 s[18:19], v14, v184
	v_add_u32_e32 v14, 0xffffffb2, v0
	v_cmp_le_i32_e64 s[20:21], v14, v184
	v_add_u32_e32 v14, 0xffffff93, v0
	s_nop 0
	v_cndmask_b32_e64 v105, v194, v105, s[20:21]
	v_cmp_le_i32_e64 s[20:21], v14, v184
	v_add_u32_e32 v14, 0xffffffb3, v0
	v_cmp_le_i32_e64 s[22:23], v14, v184
	v_add_u32_e32 v14, 0xffffff94, v0
	s_nop 0
	v_cndmask_b32_e64 v106, v194, v106, s[22:23]
	v_cmp_le_i32_e64 s[22:23], v14, v184
	v_add_u32_e32 v14, 0xffffffb4, v0
	v_cmp_le_i32_e64 s[24:25], v14, v184
	v_add_u32_e32 v14, 0xffffff99, v0
	s_nop 0
	v_cndmask_b32_e64 v107, v194, v107, s[24:25]
	v_cmp_le_i32_e64 s[24:25], v14, v184
	v_add_u32_e32 v14, 0xffffffb9, v0
	v_cmp_le_i32_e64 s[26:27], v14, v184
	v_add_u32_e32 v14, 0xffffff9a, v0
	s_nop 0
	v_cndmask_b32_e64 v108, v194, v108, s[26:27]
	v_cmp_le_i32_e64 s[26:27], v14, v184
	v_add_u32_e32 v14, 0xffffffba, v0
	v_cmp_le_i32_e64 s[28:29], v14, v184
	v_add_u32_e32 v14, 0xffffff9b, v0
	s_nop 0
	v_cndmask_b32_e64 v109, v194, v109, s[28:29]
	v_cmp_le_i32_e64 s[28:29], v14, v184
	v_add_u32_e32 v14, 0xffffffbb, v0
	v_cmp_le_i32_e64 s[30:31], v14, v184
	v_add_u32_e32 v14, 0xffffff9c, v0
	v_add_u32_e32 v0, 0xffffffbc, v0
	v_cndmask_b32_e64 v110, v194, v110, s[30:31]
	v_cmp_le_i32_e64 s[30:31], v14, v184
	v_cmp_gt_i32_e64 s[34:35], v0, v184
	s_and_saveexec_b64 s[48:49], s[34:35]
	v_mov_b32_e32 v111, s59
	s_or_b64 exec, exec, s[48:49]
	v_cndmask_b32_e64 v113, v194, v113, s[2:3]
	v_cndmask_b32_e32 v112, v194, v112, vcc
	v_cndmask_b32_e64 v114, v194, v114, s[4:5]
	v_cndmask_b32_e64 v115, v194, v115, s[6:7]
	v_cndmask_b32_e64 v116, v194, v116, s[8:9]
	v_cndmask_b32_e64 v117, v194, v117, s[10:11]
	v_cndmask_b32_e64 v118, v194, v118, s[12:13]
	v_cndmask_b32_e64 v119, v194, v119, s[14:15]
	v_cndmask_b32_e64 v120, v194, v120, s[16:17]
	v_cndmask_b32_e64 v121, v194, v121, s[18:19]
	v_cndmask_b32_e64 v122, v194, v122, s[20:21]
	v_cndmask_b32_e64 v123, v194, v123, s[22:23]
	v_cndmask_b32_e64 v124, v194, v124, s[24:25]
	v_cndmask_b32_e64 v125, v194, v125, s[26:27]
	v_cndmask_b32_e64 v126, v194, v126, s[28:29]
	v_cndmask_b32_e64 v127, v194, v127, s[30:31]

.LBB0_685:
	s_mulk_i32 s71, 0x3400
	s_add_i32 s3, s71, 0
	s_xor_b32 s2, s69, 2
	v_add_u32_e32 v0, s3, v192
	s_mulk_i32 s2, 0x2400
	s_waitcnt vmcnt(5)
	ds_write_b128 v0, v[168:171]
	v_add_u32_e32 v0, s3, v185
	s_waitcnt vmcnt(4)
	ds_write_b128 v0, v[164:167] offset:128
	v_add_u32_e32 v0, s2, v193
	s_add_i32 s2, s67, 6
	s_min_i32 s2, s2, s66
	s_mov_b32 s3, s47
	v_add_u32_e32 v0, 0xd000, v0
	s_lshl_b64 s[4:5], s[2:3], 16
	s_lshl_b64 s[2:3], s[2:3], 12
	s_waitcnt vmcnt(3)
	ds_write2_b64 v0, v[160:161], v[162:163] offset1:2
	v_lshl_add_u64 v[2:3], v[186:187], 0, s[4:5]
	v_lshl_add_u64 v[4:5], v[188:189], 0, s[2:3]
	s_lshl_b64 s[2:3], s[46:47], 7
	global_load_dwordx4 v[168:171], v[2:3], off
	global_load_dwordx4 v[164:167], v[4:5], off
	v_lshl_add_u64 v[2:3], v[190:191], 0, s[2:3]
	global_load_dwordx4 v[160:163], v[2:3], off
	s_add_i32 s46, s67, 2
	s_cmp_ge_i32 s67, s65
	s_cbranch_scc1 .LBB0_696
	s_and_b32 s2, s46, 2
	s_mulk_i32 s2, 0x3400
	v_add_u32_e32 v0, s2, v196
	ds_read_b128 v[2:5], v0
	ds_read_b128 v[6:9], v0 offset:6656
	s_waitcnt lgkmcnt(1)
	v_mfma_f32_32x32x16_bf16 v[112:127], v[2:5], v[128:131], v[48:63]
	ds_read_b128 v[10:13], v0 offset:32
	ds_read_b128 v[202:205], v0 offset:6688
	v_add_f32_e32 v211, 0, v80
	v_add_f32_e32 v210, 0, v81
	v_cvt_pk_bf16_f32 v176, v80, v81
	s_waitcnt lgkmcnt(2)
	v_mfma_f32_32x32x16_bf16 v[96:111], v[6:9], v[128:131], v[48:63]
	v_add_f32_e32 v211, v82, v211
	v_add_f32_e32 v210, v83, v210
	v_add_f32_e32 v211, v84, v211
	v_cvt_pk_bf16_f32 v177, v82, v83
	s_waitcnt lgkmcnt(1)
	v_mfma_f32_32x32x16_bf16 v[112:127], v[10:13], v[132:135], v[112:127]
	ds_read_b128 v[2:5], v0 offset:64
	ds_read_b128 v[6:9], v0 offset:6720
	v_add_f32_e32 v210, v85, v210
	v_add_f32_e32 v211, v86, v211
	v_add_f32_e32 v210, v87, v210
	v_cvt_pk_bf16_f32 v178, v84, v85
	v_cvt_pk_bf16_f32 v179, v86, v87
	s_waitcnt lgkmcnt(2)
	v_mfma_f32_32x32x16_bf16 v[96:111], v[202:205], v[132:135], v[96:111]
	v_add_f32_e32 v211, v88, v211
	v_add_f32_e32 v210, v89, v210
	v_cvt_pk_bf16_f32 v10, v88, v89
	s_waitcnt lgkmcnt(1)
	v_mfma_f32_32x32x16_bf16 v[112:127], v[2:5], v[136:139], v[112:127]
	ds_read_b128 v[80:83], v0 offset:96
	ds_read_b128 v[202:205], v0 offset:6752
	v_add_f32_e32 v211, v90, v211
	v_add_f32_e32 v210, v91, v210
	v_add_f32_e32 v211, v92, v211
	v_cvt_pk_bf16_f32 v11, v90, v91
	s_waitcnt lgkmcnt(2)
	v_mfma_f32_32x32x16_bf16 v[96:111], v[6:9], v[136:139], v[96:111]
	v_add_f32_e32 v210, v93, v210
	v_add_f32_e32 v211, v94, v211
	v_add_f32_e32 v210, v95, v210
	v_cvt_pk_bf16_f32 v12, v92, v93
	v_cvt_pk_bf16_f32 v13, v94, v95
	s_waitcnt lgkmcnt(1)
	v_mfma_f32_32x32x16_bf16 v[112:127], v[80:83], v[140:143], v[112:127]
	ds_read_b128 v[2:5], v0 offset:128
	ds_read_b128 v[206:209], v0 offset:6784
	v_add_f32_e32 v211, v16, v211
	v_add_f32_e32 v210, v17, v210
	v_cvt_pk_bf16_f32 v6, v16, v17
	s_waitcnt lgkmcnt(2)
	v_mfma_f32_32x32x16_bf16 v[96:111], v[202:205], v[140:143], v[96:111]
	v_add_f32_e32 v211, v18, v211
	v_add_f32_e32 v210, v19, v210
	v_add_f32_e32 v211, v20, v211
	v_cvt_pk_bf16_f32 v7, v18, v19
	s_waitcnt lgkmcnt(1)
	v_mfma_f32_32x32x16_bf16 v[112:127], v[2:5], v[144:147], v[112:127]
	ds_read_b128 v[14:17], v0 offset:160
	ds_read_b128 v[80:83], v0 offset:6816
	v_add_f32_e32 v210, v21, v210
	v_add_f32_e32 v211, v22, v211
	v_add_f32_e32 v210, v23, v210
	v_cvt_pk_bf16_f32 v8, v20, v21
	v_cvt_pk_bf16_f32 v9, v22, v23
	s_waitcnt lgkmcnt(2)
	v_mfma_f32_32x32x16_bf16 v[96:111], v[206:209], v[144:147], v[96:111]
	v_add_f32_e32 v211, v24, v211
	v_add_f32_e32 v210, v25, v210
	v_cvt_pk_bf16_f32 v2, v24, v25
	s_waitcnt lgkmcnt(1)
	v_mfma_f32_32x32x16_bf16 v[112:127], v[14:17], v[148:151], v[112:127]
	v_add_f32_e32 v211, v26, v211
	v_add_f32_e32 v210, v27, v210
	v_add_f32_e32 v211, v28, v211
	v_cvt_pk_bf16_f32 v3, v26, v27
	s_waitcnt lgkmcnt(0)
	v_mfma_f32_32x32x16_bf16 v[96:111], v[80:83], v[148:151], v[96:111]
	v_add_f32_e32 v210, v29, v210
	v_add_f32_e32 v211, v30, v211
	v_add_f32_e32 v210, v31, v210
	v_add_f32_e32 v0, v210, v211
	v_cvt_pk_bf16_f32 v4, v28, v29
	v_cvt_pk_bf16_f32 v5, v30, v31
	s_mul_i32 s4, s69, 0x2400
	v_add_u32_e32 v206, s4, v200
	ds_read_b128 v[16:19], v206 offset:53248
	ds_read_b128 v[202:205], v206 offset:57856
	s_cmp_ge_i32 s70, s65
	v_add_f32_e32 v201, v201, v0
	s_cbranch_scc1 .LBB0_693
	s_cmp_le_i32 s68, s63
	s_cbranch_scc1 .LBB0_691
	v_add_u32_e32 v0, s68, v197
	v_subrev_u32_e32 v15, 31, v0
	v_subrev_u32_e32 v14, 63, v0
	v_cmp_le_i32_e64 s[2:3], v15, v184
	v_cmp_le_i32_e32 vcc, v14, v184
	s_nop 0
	v_cndmask_b32_e64 v96, v194, v96, s[2:3]
	v_cmp_lt_i32_e64 s[2:3], v14, v184
	v_subrev_u32_e32 v14, 30, v0
	v_cmp_le_i32_e64 s[4:5], v14, v184
	v_subrev_u32_e32 v14, 61, v0
	s_nop 0
	v_cndmask_b32_e64 v97, v194, v97, s[4:5]
	v_cmp_le_i32_e64 s[4:5], v14, v184
	v_subrev_u32_e32 v14, 29, v0
	v_cmp_le_i32_e64 s[6:7], v14, v184
	v_subrev_u32_e32 v14, 60, v0
	s_nop 0
	v_cndmask_b32_e64 v98, v194, v98, s[6:7]
	v_cmp_le_i32_e64 s[6:7], v14, v184
	v_subrev_u32_e32 v14, 28, v0
	v_cmp_le_i32_e64 s[8:9], v14, v184
	v_subrev_u32_e32 v14, 55, v0
	s_nop 0
	v_cndmask_b32_e64 v99, v194, v99, s[8:9]
	v_cmp_le_i32_e64 s[8:9], v14, v184
	v_subrev_u32_e32 v14, 23, v0
	v_cmp_le_i32_e64 s[10:11], v14, v184
	v_subrev_u32_e32 v14, 54, v0
	s_nop 0
	v_cndmask_b32_e64 v100, v194, v100, s[10:11]
	v_cmp_le_i32_e64 s[10:11], v14, v184
	v_subrev_u32_e32 v14, 22, v0
	v_cmp_le_i32_e64 s[12:13], v14, v184
	v_subrev_u32_e32 v14, 53, v0
	s_nop 0
	v_cndmask_b32_e64 v101, v194, v101, s[12:13]
	v_cmp_le_i32_e64 s[12:13], v14, v184
	v_subrev_u32_e32 v14, 21, v0
	v_cmp_le_i32_e64 s[14:15], v14, v184
	v_subrev_u32_e32 v14, 52, v0
	s_nop 0
	v_cndmask_b32_e64 v102, v194, v102, s[14:15]
	v_cmp_le_i32_e64 s[14:15], v14, v184
	v_subrev_u32_e32 v14, 20, v0
	v_cmp_le_i32_e64 s[16:17], v14, v184
	v_subrev_u32_e32 v14, 47, v0
	s_nop 0
	v_cndmask_b32_e64 v103, v194, v103, s[16:17]
	v_cmp_le_i32_e64 s[16:17], v14, v184
	v_add_u32_e32 v14, -15, v0
	v_cmp_le_i32_e64 s[18:19], v14, v184
	v_subrev_u32_e32 v14, 46, v0
	s_nop 0
	v_cndmask_b32_e64 v104, v194, v104, s[18:19]
	v_cmp_le_i32_e64 s[18:19], v14, v184
	v_add_u32_e32 v14, -14, v0
	v_cmp_le_i32_e64 s[20:21], v14, v184
	v_subrev_u32_e32 v14, 45, v0
	s_nop 0
	v_cndmask_b32_e64 v105, v194, v105, s[20:21]
	v_cmp_le_i32_e64 s[20:21], v14, v184
	v_add_u32_e32 v14, -13, v0
	v_cmp_le_i32_e64 s[22:23], v14, v184
	v_subrev_u32_e32 v14, 44, v0
	s_nop 0
	v_cndmask_b32_e64 v106, v194, v106, s[22:23]
	v_cmp_le_i32_e64 s[22:23], v14, v184
	v_add_u32_e32 v14, -12, v0
	v_cmp_le_i32_e64 s[24:25], v14, v184
	v_subrev_u32_e32 v14, 39, v0
	s_nop 0
	v_cndmask_b32_e64 v107, v194, v107, s[24:25]
	v_cmp_le_i32_e64 s[24:25], v14, v184
	v_add_u32_e32 v14, -7, v0
	v_cmp_le_i32_e64 s[26:27], v14, v184
	v_subrev_u32_e32 v14, 38, v0
	s_nop 0
	v_cndmask_b32_e64 v108, v194, v108, s[26:27]
	v_cmp_le_i32_e64 s[26:27], v14, v184
	v_add_u32_e32 v14, -6, v0
	v_cmp_le_i32_e64 s[28:29], v14, v184
	v_subrev_u32_e32 v14, 37, v0
	s_nop 0
	v_cndmask_b32_e64 v109, v194, v109, s[28:29]
	v_cmp_le_i32_e64 s[28:29], v14, v184
	v_add_u32_e32 v14, -5, v0
	v_cmp_le_i32_e64 s[30:31], v14, v184
	v_subrev_u32_e32 v14, 36, v0
	v_add_u32_e32 v0, -4, v0
	v_cndmask_b32_e64 v110, v194, v110, s[30:31]
	v_cmp_le_i32_e64 s[30:31], v14, v184
	v_cmp_gt_i32_e64 s[34:35], v0, v184
	s_and_saveexec_b64 s[48:49], s[34:35]
	v_mov_b32_e32 v111, s59
	s_or_b64 exec, exec, s[48:49]
	v_cndmask_b32_e64 v113, v194, v113, s[2:3]
	v_cndmask_b32_e32 v112, v194, v112, vcc
	v_cndmask_b32_e64 v114, v194, v114, s[4:5]
	v_cndmask_b32_e64 v115, v194, v115, s[6:7]
	v_cndmask_b32_e64 v116, v194, v116, s[8:9]
	v_cndmask_b32_e64 v117, v194, v117, s[10:11]
	v_cndmask_b32_e64 v118, v194, v118, s[12:13]
	v_cndmask_b32_e64 v119, v194, v119, s[14:15]
	v_cndmask_b32_e64 v120, v194, v120, s[16:17]
	v_cndmask_b32_e64 v121, v194, v121, s[18:19]
	v_cndmask_b32_e64 v122, v194, v122, s[20:21]
	v_cndmask_b32_e64 v123, v194, v123, s[22:23]
	v_cndmask_b32_e64 v124, v194, v124, s[24:25]
	v_cndmask_b32_e64 v125, v194, v125, s[26:27]
	v_cndmask_b32_e64 v126, v194, v126, s[28:29]
	v_cndmask_b32_e64 v127, v194, v127, s[30:31]
